# plus prep phase: trailing-window row loads also issued at the top of the token body (one load round trip per token)
# speedup vs baseline: 1.0616x; 1.0026x over previous
; __device__ __forceinline__ float bf_lo(unsigned u) { return __uint_as_float(u << 16); }
; __device__ __forceinline__ float bf_hi(unsigned u) { return __uint_as_float(u & 0xffff0000u); }
; __global__ void __launch_bounds__(NTHR) fwd_kernel(Args args) {
;     ...
;                 { const int tp = t & (SEQ - 1), wdw = 2 << (lane >> 4), cnt = (tp + 1) < wdw ? (tp + 1) : wdw;
;                   float a[8]; const u32x4 cur = *(const u32x4*)(zr + 512 + 8 * lane);
; #pragma unroll
;                   for (int e = 0; e < 4; ++e) { a[2 * e] = bf_lo(cur[e]); a[2 * e + 1] = bf_hi(cur[e]); }
;                   float sm[8];
; #pragma unroll
;                   for (int e = 0; e < 8; ++e) sm[e] = a[e];
;                   for (int j = 1; j < cnt; ++j) { const u32x4 pv = *(const u32x4*)(zr - (size_t)j * 1024 + 512 + 8 * lane);
; #pragma unroll
;                       for (int e = 0; e < 4; ++e) { sm[2 * e] += bf_lo(pv[e]); sm[2 * e + 1] += bf_hi(pv[e]); } }
.LBB0_461:
	s_ashr_i32 s43, s42, 31
	s_lshl_b64 s[44:45], s[42:43], 11
	s_add_u32 s18, s72, s44
	s_addc_u32 s19, s73, s45
	v_lshlrev_b32_e32 v2, 1, v0
	v_lshl_add_u64 v[26:27], s[18:19], 0, v[2:3]
	s_mov_b32 s12, 0x7400000
	v_add_co_u32_e32 v26, vcc, s12, v26
	s_add_u32 s44, s4, s44
	s_nop 0
	v_addc_co_u32_e32 v27, vcc, 0, v27, vcc
	flat_load_dwordx4 v[26:29], v[26:27] offset:1024
	s_addc_u32 s45, s5, s45
	v_mov_b32_e32 v144, v24
	v_mov_b32_e32 v145, v3
	v_lshl_add_u64 v[138:139], s[44:45], 0, v[144:145]
	global_load_dwordx2 v[124:125], v[138:139], off
	global_load_dwordx4 v[128:131], v[4:5], off
	v_lshl_add_u64 v[146:147], v[138:139], 0, v[18:19]
	global_load_dword v126, v[146:147], off offset:512
	global_load_dwordx2 v[132:133], v[8:9], off
	v_lshl_add_u64 v[150:151], s[44:45], 0, v[2:3]
	global_load_dwordx4 v[140:143], v[150:151], off offset:1024
	v_lshl_add_u64 v[148:149], v[146:147], 0, v[20:21]
	s_lshl_b64 s[98:99], s[42:43], 2
	s_add_u32 s98, s36, s98
	s_addc_u32 s99, s37, s99
	s_and_saveexec_b64 s[46:47], s[40:41]
	global_load_ushort v134, v[148:149], off offset:768
	global_load_ushort v135, v[148:149], off offset:800
	global_load_dword v136, v[12:13], off
	global_load_dword v137, v3, s[98:99]
	s_or_b64 exec, exec, s[46:47]
	s_and_b32 s100, s42, 0x1fff
	s_cmp_eq_u32 s100, 0
	s_cbranch_scc1 .Lpool_pre_skip
	s_and_b32 s100, s6, 0x1fff
	s_add_i32 s100, s100, 1
	v_min_u32_e32 v152, s100, v1
	v_max_u32_e32 v152, 2, v152
	v_add_u32_e32 v152, -1, v152
	v_mov_b64_e32 v[154:155], v[22:23]
	s_mov_b64 s[100:101], exec
	s_movk_i32 s98, 0xf800
	s_mov_b32 s99, -1
	global_load_dwordx4 v[64:67], v[154:155], off
	v_lshl_add_u64 v[154:155], v[154:155], 0, s[98:99]
	v_cmp_le_u32_e32 vcc, 2, v152
	s_nop 1
	s_and_b64 exec, s[100:101], vcc
	s_cbranch_execz .Lpool_pre_issued
	global_load_dwordx4 v[68:71], v[154:155], off
	v_lshl_add_u64 v[154:155], v[154:155], 0, s[98:99]
	v_cmp_le_u32_e32 vcc, 3, v152
	s_nop 1
	s_and_b64 exec, s[100:101], vcc
	s_cbranch_execz .Lpool_pre_issued
	global_load_dwordx4 v[72:75], v[154:155], off
	v_lshl_add_u64 v[154:155], v[154:155], 0, s[98:99]
	v_cmp_le_u32_e32 vcc, 4, v152
	s_nop 1
	s_and_b64 exec, s[100:101], vcc
	s_cbranch_execz .Lpool_pre_issued
	global_load_dwordx4 v[76:79], v[154:155], off
	v_lshl_add_u64 v[154:155], v[154:155], 0, s[98:99]
	v_cmp_le_u32_e32 vcc, 5, v152
	s_nop 1
	s_and_b64 exec, s[100:101], vcc
	s_cbranch_execz .Lpool_pre_issued
	global_load_dwordx4 v[80:83], v[154:155], off
	v_lshl_add_u64 v[154:155], v[154:155], 0, s[98:99]
	v_cmp_le_u32_e32 vcc, 6, v152
	s_nop 1
	s_and_b64 exec, s[100:101], vcc
	s_cbranch_execz .Lpool_pre_issued
	global_load_dwordx4 v[84:87], v[154:155], off
	v_lshl_add_u64 v[154:155], v[154:155], 0, s[98:99]
	v_cmp_le_u32_e32 vcc, 7, v152
	s_nop 1
	s_and_b64 exec, s[100:101], vcc
	s_cbranch_execz .Lpool_pre_issued
	global_load_dwordx4 v[88:91], v[154:155], off
	v_lshl_add_u64 v[154:155], v[154:155], 0, s[98:99]
	v_cmp_le_u32_e32 vcc, 8, v152
	s_nop 1
	s_and_b64 exec, s[100:101], vcc
	s_cbranch_execz .Lpool_pre_issued
	global_load_dwordx4 v[92:95], v[154:155], off
	v_lshl_add_u64 v[154:155], v[154:155], 0, s[98:99]
	v_cmp_le_u32_e32 vcc, 9, v152
	s_nop 1
	s_and_b64 exec, s[100:101], vcc
	s_cbranch_execz .Lpool_pre_issued
	global_load_dwordx4 v[96:99], v[154:155], off
	v_lshl_add_u64 v[154:155], v[154:155], 0, s[98:99]
	v_cmp_le_u32_e32 vcc, 10, v152
	s_nop 1
	s_and_b64 exec, s[100:101], vcc
	s_cbranch_execz .Lpool_pre_issued
	global_load_dwordx4 v[100:103], v[154:155], off
	v_lshl_add_u64 v[154:155], v[154:155], 0, s[98:99]
	v_cmp_le_u32_e32 vcc, 11, v152
	s_nop 1
	s_and_b64 exec, s[100:101], vcc
	s_cbranch_execz .Lpool_pre_issued
	global_load_dwordx4 v[104:107], v[154:155], off
	v_lshl_add_u64 v[154:155], v[154:155], 0, s[98:99]
	v_cmp_le_u32_e32 vcc, 12, v152
	s_nop 1
	s_and_b64 exec, s[100:101], vcc
	s_cbranch_execz .Lpool_pre_issued
	global_load_dwordx4 v[108:111], v[154:155], off
	v_lshl_add_u64 v[154:155], v[154:155], 0, s[98:99]
	v_cmp_le_u32_e32 vcc, 13, v152
	s_nop 1
	s_and_b64 exec, s[100:101], vcc
	s_cbranch_execz .Lpool_pre_issued
	global_load_dwordx4 v[112:115], v[154:155], off
	v_lshl_add_u64 v[154:155], v[154:155], 0, s[98:99]
	v_cmp_le_u32_e32 vcc, 14, v152
	s_nop 1
	s_and_b64 exec, s[100:101], vcc
	s_cbranch_execz .Lpool_pre_issued
	global_load_dwordx4 v[116:119], v[154:155], off
	v_lshl_add_u64 v[154:155], v[154:155], 0, s[98:99]
	v_cmp_le_u32_e32 vcc, 15, v152
	s_nop 1
	s_and_b64 exec, s[100:101], vcc
	s_cbranch_execz .Lpool_pre_issued
	global_load_dwordx4 v[120:123], v[154:155], off
	v_lshl_add_u64 v[154:155], v[154:155], 0, s[98:99]
; __device__ __forceinline__ unsigned cvt_pk_bf16(float lo, float hi) { f32x2_cv v = {lo, hi}; bf16x2_cv b = __builtin_convertvector(v, bf16x2_cv); return __builtin_bit_cast(unsigned, b); }
; __device__ __forceinline__ float bf_lo(unsigned u) { return __uint_as_float(u << 16); }
; __device__ __forceinline__ float bf_hi(unsigned u) { return __uint_as_float(u & 0xffff0000u); }
; __global__ void __launch_bounds__(NTHR) fwd_kernel(Args args) {
;     ...
;                 { const u32x4 kv = *(const u32x4*)((const bf16*)(ws + WS_Z2) + (size_t)t * 1024 + 512 + 8 * lane); float ss = 0.f;
; #pragma unroll
;                   for (int e = 0; e < 4; ++e) { const float x = bf_lo(kv[e]), y = bf_hi(kv[e]); ss += x * x + y * y; }
;                   ss += __shfl_xor(ss, 1); ss += __shfl_xor(ss, 2);
;                   if (t < SEQ) kmx0 = fmaxf(kmx0, ss); else kmx1 = fmaxf(kmx1, ss); }
;                 { const u32x2 v = ((const u32x2*)zr)[lane]; float x0 = bf_lo(v.x), x1 = bf_hi(v.x), x2 = bf_lo(v.y), x3 = bf_hi(v.y);
;                   const float rs = __builtin_amdgcn_rsqf(wave_sum(x0 * x0 + x1 * x1 + x2 * x2 + x3 * x3) * (1.0f / 256.0f) + 1e-6f); const f32x4 gq = ((const f32x4*)q_norm)[lane];
;                   u32x2 o; o.x = cvt_pk_bf16(x0 * rs * gq.x, x1 * rs * gq.y); o.y = cvt_pk_bf16(x2 * rs * gq.z, x3 * rs * gq.w); ((u32x2*)(CQN + (size_t)t * 256))[lane] = o; }
;                 { const unsigned v = ((const unsigned*)(zr + 256))[lane]; float x0 = bf_lo(v), x1 = bf_hi(v);
;                   const float rs = __builtin_amdgcn_rsqf(wave_sum(x0 * x0 + x1 * x1) * (1.0f / 128.0f) + 1e-6f);
;                   ((unsigned*)(CKVN + (size_t)t * 128))[lane] = cvt_pk_bf16(x0 * rs * kv_norm[2 * lane], x1 * rs * kv_norm[2 * lane + 1]); }
;                 if (lane < 16) { const float x1 = bf_lo((unsigned)zr[384 + lane]), x2 = bf_lo((unsigned)zr[400 + lane]); float s, c; sincos_acc((float)pos[t] * ((const float*)(ws + WS_TAB))[lane], s, c);
;                   KR[(size_t)t * 32 + lane] = (bf16)(cvt_pk_bf16(x1 * c - x2 * s, 0.f) & 0xffffu); KR[(size_t)t * 32 + 16 + lane] = (bf16)(cvt_pk_bf16(x2 * c + x1 * s, 0.f) & 0xffffu); }
.Lpool_pre_issued:
	s_mov_b64 exec, s[100:101]
.Lpool_pre_skip:
	s_lshl_b64 s[18:19], s[42:43], 9
	s_waitcnt vmcnt(0) lgkmcnt(0)
	v_lshlrev_b32_e32 v31, 16, v27
	v_lshlrev_b32_e32 v30, 16, v26
	v_and_b32_e32 v27, 0xffff0000, v27
	v_and_b32_e32 v26, 0xffff0000, v26
	v_pk_mul_f32 v[26:27], v[26:27], v[26:27]
	s_nop 0
	v_pk_fma_f32 v[26:27], v[30:31], v[30:31], v[26:27]
	v_lshlrev_b32_e32 v31, 16, v29
	v_lshlrev_b32_e32 v30, 16, v28
	v_and_b32_e32 v29, 0xffff0000, v29
	v_and_b32_e32 v28, 0xffff0000, v28
	v_pk_mul_f32 v[28:29], v[28:29], v[28:29]
	v_add_f32_e32 v25, v26, v27
	v_pk_fma_f32 v[28:29], v[30:31], v[30:31], v[28:29]
	s_nop 0
	v_add_f32_e32 v25, v25, v28
	v_add_f32_e32 v25, v25, v29
	ds_bpermute_b32 v26, v44, v25
	s_waitcnt lgkmcnt(0)
	v_add_f32_e32 v52, v25, v26
	v_mov_b32_e32 v25, v3
	v_lshl_add_u64 v[30:31], s[44:45], 0, v[24:25]
	v_mov_b32_e32 v32, v124
	v_mov_b32_e32 v33, v125
	v_mov_b32_e32 v26, v128
	v_mov_b32_e32 v27, v129
	v_mov_b32_e32 v28, v130
	v_mov_b32_e32 v29, v131
	ds_bpermute_b32 v53, v45, v52
	s_waitcnt lgkmcnt(0)
	v_lshlrev_b32_e32 v38, 16, v32
	v_and_b32_e32 v39, 0xffff0000, v32
	v_lshlrev_b32_e32 v34, 16, v33
	v_and_b32_e32 v35, 0xffff0000, v33
	v_pk_mul_f32 v[32:33], v[38:39], v[38:39]
	v_pk_mul_f32 v[36:37], v[34:35], v[34:35]
	v_add_f32_e32 v25, v32, v33
	v_add_f32_e32 v25, v36, v25
	v_add_f32_e32 v25, v37, v25
	ds_bpermute_b32 v32, v44, v25
	s_waitcnt lgkmcnt(0)
	v_add_f32_e32 v25, v25, v32
	ds_bpermute_b32 v32, v45, v25
	s_waitcnt lgkmcnt(0)
	v_add_f32_e32 v25, v25, v32
	ds_bpermute_b32 v32, v46, v25
	s_waitcnt lgkmcnt(0)
	v_add_f32_e32 v25, v25, v32
	ds_bpermute_b32 v32, v47, v25
	s_waitcnt lgkmcnt(0)
	v_add_f32_e32 v25, v25, v32
	ds_bpermute_b32 v32, v48, v25
	s_waitcnt lgkmcnt(0)
	v_add_f32_e32 v25, v25, v32
	ds_bpermute_b32 v32, v49, v25
	s_waitcnt lgkmcnt(0)
	v_add_f32_e32 v25, v25, v32
	v_fmamk_f32 v25, v25, 0x3b800000, v212
	v_rsq_f32_e32 v32, v25
	s_nop 0
	v_pk_mul_f32 v[36:37], v[32:33], v[38:39] op_sel_hi:[0,1]
	v_pk_mul_f32 v[32:33], v[32:33], v[34:35] op_sel_hi:[0,1]
	v_pk_mul_f32 v[26:27], v[26:27], v[36:37]
	v_pk_mul_f32 v[28:29], v[28:29], v[32:33]
	v_cvt_pk_bf16_f32 v26, v26, v27
	v_cvt_pk_bf16_f32 v27, v28, v29
	v_lshl_add_u64 v[28:29], v[6:7], 0, s[18:19]
	global_store_dwordx2 v[28:29], v[26:27], off
	v_lshl_add_u64 v[26:27], v[30:31], 0, v[18:19]
	v_mov_b32_e32 v25, v126
	s_lshl_b64 s[18:19], s[42:43], 8
	s_waitcnt lgkmcnt(0)
	v_lshlrev_b32_e32 v28, 16, v25
	v_and_b32_e32 v29, 0xffff0000, v25
	v_pk_mul_f32 v[30:31], v[28:29], v[28:29]
	s_nop 0
	v_add_f32_e32 v25, v30, v31
	ds_bpermute_b32 v30, v44, v25
	s_waitcnt lgkmcnt(0)
	v_add_f32_e32 v25, v25, v30
	ds_bpermute_b32 v30, v45, v25
	s_waitcnt lgkmcnt(0)
	v_add_f32_e32 v25, v25, v30
	ds_bpermute_b32 v30, v46, v25
	s_waitcnt lgkmcnt(0)
	v_add_f32_e32 v25, v25, v30
	ds_bpermute_b32 v30, v47, v25
	s_waitcnt lgkmcnt(0)
	v_add_f32_e32 v25, v25, v30
	ds_bpermute_b32 v30, v48, v25
	s_waitcnt lgkmcnt(0)
	v_add_f32_e32 v25, v25, v30
	ds_bpermute_b32 v30, v49, v25
	s_waitcnt lgkmcnt(0)
	v_add_f32_e32 v25, v25, v30
	v_fmamk_f32 v25, v25, 0x3c000000, v212
	v_rsq_f32_e32 v30, v25
	s_nop 0
	v_pk_mul_f32 v[28:29], v[30:31], v[28:29] op_sel_hi:[0,1]
	v_mov_b32_e32 v30, v132
	v_mov_b32_e32 v31, v133
	v_pk_mul_f32 v[28:29], v[30:31], v[28:29]
	s_nop 0
	v_cvt_pk_bf16_f32 v25, v28, v29
	v_lshl_add_u64 v[28:29], v[10:11], 0, s[18:19]
	global_store_dword v[28:29], v25, off
	s_and_saveexec_b64 s[46:47], s[40:41]
	s_cbranch_execz .LBB0_463
	v_lshl_add_u64 v[26:27], v[26:27], 0, v[20:21]
	v_mov_b32_e32 v25, v134
	s_lshl_b64 s[18:19], s[42:43], 2
	v_mov_b32_e32 v26, v135
	s_add_u32 s18, s36, s18
	s_addc_u32 s19, s37, s19
	v_mov_b32_e32 v27, v136
	s_waitcnt lgkmcnt(0)
	v_lshlrev_b32_e32 v25, 16, v25
	v_lshlrev_b32_e32 v30, 16, v26
	v_mov_b32_e32 v26, v137
	s_mov_b32 s18, 0x6dc9c883
	s_mov_b32 s19, 0x3fc45f30
	v_cvt_f32_i32_e32 v26, v26
	v_mul_f32_e32 v26, v27, v26
	v_cvt_f64_f32_e32 v[26:27], v26
	v_mul_f64 v[28:29], v[26:27], s[18:19]
	v_rndne_f64_e32 v[28:29], v[28:29]
	v_fma_f64 v[26:27], v[26:27], s[18:19], -v[28:29]
	v_cvt_f32_f64_e32 v26, v[26:27]
	v_sin_f32_e32 v28, v26
	v_cos_f32_e32 v29, v26
	s_lshl_b64 s[18:19], s[42:43], 6
	v_mul_f32_e32 v26, v28, v30
	v_fma_f32 v26, v29, v25, -v26
	v_mul_f32_e32 v25, v28, v25
	v_fmac_f32_e32 v25, v29, v30
	v_cvt_pk_bf16_f32 v31, v26, s0
	v_lshl_add_u64 v[26:27], v[14:15], 0, s[18:19]
	v_cvt_pk_bf16_f32 v25, v25, s0
	global_store_short v[26:27], v31, off
	global_store_short v[26:27], v25, off offset:32

; __device__ __forceinline__ float bf_lo(unsigned u) { return __uint_as_float(u << 16); }
; __device__ __forceinline__ float bf_hi(unsigned u) { return __uint_as_float(u & 0xffff0000u); }
; __global__ void __launch_bounds__(NTHR) fwd_kernel(Args args) {
;     ...
;                   for (int j = 1; j < cnt; ++j) { const u32x4 pv = *(const u32x4*)(zr - (size_t)j * 1024 + 512 + 8 * lane);
; #pragma unroll
;                       for (int e = 0; e < 4; ++e) { sm[2 * e] += bf_lo(pv[e]); sm[2 * e + 1] += bf_hi(pv[e]); } }
.LBB0_465:
	s_mov_b64 s[44:45], exec
	v_lshlrev_b32_e32 v58, 16, v64
	v_and_b32_e32 v59, 0xffff0000, v64
	v_lshlrev_b32_e32 v54, 16, v65
	v_and_b32_e32 v55, 0xffff0000, v65
	v_pk_add_f32 v[32:33], v[32:33], v[54:55]
	v_lshlrev_b32_e32 v54, 16, v66
	v_and_b32_e32 v55, 0xffff0000, v66
	v_pk_add_f32 v[38:39], v[38:39], v[54:55]
	v_lshlrev_b32_e32 v54, 16, v67
	v_and_b32_e32 v55, 0xffff0000, v67
	v_pk_add_f32 v[36:37], v[36:37], v[58:59]
	v_pk_add_f32 v[40:41], v[40:41], v[54:55]
	v_cmp_le_u32_e32 vcc, 2, v2
	s_nop 1
	s_and_b64 exec, s[44:45], vcc
	s_cbranch_execz .Lpool_done
	v_lshlrev_b32_e32 v58, 16, v68
	v_and_b32_e32 v59, 0xffff0000, v68
	v_lshlrev_b32_e32 v54, 16, v69
	v_and_b32_e32 v55, 0xffff0000, v69
	v_pk_add_f32 v[32:33], v[32:33], v[54:55]
	v_lshlrev_b32_e32 v54, 16, v70
	v_and_b32_e32 v55, 0xffff0000, v70
	v_pk_add_f32 v[38:39], v[38:39], v[54:55]
	v_lshlrev_b32_e32 v54, 16, v71
	v_and_b32_e32 v55, 0xffff0000, v71
	v_pk_add_f32 v[36:37], v[36:37], v[58:59]
	v_pk_add_f32 v[40:41], v[40:41], v[54:55]
	v_cmp_le_u32_e32 vcc, 3, v2
	s_nop 1
	s_and_b64 exec, s[44:45], vcc
	s_cbranch_execz .Lpool_done
	v_lshlrev_b32_e32 v58, 16, v72
	v_and_b32_e32 v59, 0xffff0000, v72
	v_lshlrev_b32_e32 v54, 16, v73
	v_and_b32_e32 v55, 0xffff0000, v73
	v_pk_add_f32 v[32:33], v[32:33], v[54:55]
	v_lshlrev_b32_e32 v54, 16, v74
	v_and_b32_e32 v55, 0xffff0000, v74
	v_pk_add_f32 v[38:39], v[38:39], v[54:55]
	v_lshlrev_b32_e32 v54, 16, v75
	v_and_b32_e32 v55, 0xffff0000, v75
	v_pk_add_f32 v[36:37], v[36:37], v[58:59]
	v_pk_add_f32 v[40:41], v[40:41], v[54:55]
	v_cmp_le_u32_e32 vcc, 4, v2
	s_nop 1
	s_and_b64 exec, s[44:45], vcc
	s_cbranch_execz .Lpool_done
	v_lshlrev_b32_e32 v58, 16, v76
	v_and_b32_e32 v59, 0xffff0000, v76
	v_lshlrev_b32_e32 v54, 16, v77
	v_and_b32_e32 v55, 0xffff0000, v77
	v_pk_add_f32 v[32:33], v[32:33], v[54:55]
	v_lshlrev_b32_e32 v54, 16, v78
	v_and_b32_e32 v55, 0xffff0000, v78
	v_pk_add_f32 v[38:39], v[38:39], v[54:55]
	v_lshlrev_b32_e32 v54, 16, v79
	v_and_b32_e32 v55, 0xffff0000, v79
	v_pk_add_f32 v[36:37], v[36:37], v[58:59]
	v_pk_add_f32 v[40:41], v[40:41], v[54:55]
	v_cmp_le_u32_e32 vcc, 5, v2
	s_nop 1
	s_and_b64 exec, s[44:45], vcc
	s_cbranch_execz .Lpool_done
	v_lshlrev_b32_e32 v58, 16, v80
	v_and_b32_e32 v59, 0xffff0000, v80
	v_lshlrev_b32_e32 v54, 16, v81
	v_and_b32_e32 v55, 0xffff0000, v81
	v_pk_add_f32 v[32:33], v[32:33], v[54:55]
	v_lshlrev_b32_e32 v54, 16, v82
	v_and_b32_e32 v55, 0xffff0000, v82
	v_pk_add_f32 v[38:39], v[38:39], v[54:55]
	v_lshlrev_b32_e32 v54, 16, v83
	v_and_b32_e32 v55, 0xffff0000, v83
	v_pk_add_f32 v[36:37], v[36:37], v[58:59]
	v_pk_add_f32 v[40:41], v[40:41], v[54:55]
	v_cmp_le_u32_e32 vcc, 6, v2
	s_nop 1
	s_and_b64 exec, s[44:45], vcc
	s_cbranch_execz .Lpool_done
	v_lshlrev_b32_e32 v58, 16, v84
	v_and_b32_e32 v59, 0xffff0000, v84
	v_lshlrev_b32_e32 v54, 16, v85
	v_and_b32_e32 v55, 0xffff0000, v85
	v_pk_add_f32 v[32:33], v[32:33], v[54:55]
	v_lshlrev_b32_e32 v54, 16, v86
	v_and_b32_e32 v55, 0xffff0000, v86
	v_pk_add_f32 v[38:39], v[38:39], v[54:55]
	v_lshlrev_b32_e32 v54, 16, v87
	v_and_b32_e32 v55, 0xffff0000, v87
	v_pk_add_f32 v[36:37], v[36:37], v[58:59]
	v_pk_add_f32 v[40:41], v[40:41], v[54:55]
	v_cmp_le_u32_e32 vcc, 7, v2
	s_nop 1
	s_and_b64 exec, s[44:45], vcc
	s_cbranch_execz .Lpool_done
	v_lshlrev_b32_e32 v58, 16, v88
	v_and_b32_e32 v59, 0xffff0000, v88
	v_lshlrev_b32_e32 v54, 16, v89
	v_and_b32_e32 v55, 0xffff0000, v89
	v_pk_add_f32 v[32:33], v[32:33], v[54:55]
	v_lshlrev_b32_e32 v54, 16, v90
	v_and_b32_e32 v55, 0xffff0000, v90
	v_pk_add_f32 v[38:39], v[38:39], v[54:55]
	v_lshlrev_b32_e32 v54, 16, v91
	v_and_b32_e32 v55, 0xffff0000, v91
	v_pk_add_f32 v[36:37], v[36:37], v[58:59]
	v_pk_add_f32 v[40:41], v[40:41], v[54:55]
	v_cmp_le_u32_e32 vcc, 8, v2
	s_nop 1
	s_and_b64 exec, s[44:45], vcc
	s_cbranch_execz .Lpool_done
; __device__ __forceinline__ float bf_lo(unsigned u) { return __uint_as_float(u << 16); }
; __device__ __forceinline__ float bf_hi(unsigned u) { return __uint_as_float(u & 0xffff0000u); }
; __global__ void __launch_bounds__(NTHR) fwd_kernel(Args args) {
;     ...
;                   for (int j = 1; j < cnt; ++j) { const u32x4 pv = *(const u32x4*)(zr - (size_t)j * 1024 + 512 + 8 * lane);
; #pragma unroll
;                       for (int e = 0; e < 4; ++e) { sm[2 * e] += bf_lo(pv[e]); sm[2 * e + 1] += bf_hi(pv[e]); } }
	v_lshlrev_b32_e32 v58, 16, v92
	v_and_b32_e32 v59, 0xffff0000, v92
	v_lshlrev_b32_e32 v54, 16, v93
	v_and_b32_e32 v55, 0xffff0000, v93
	v_pk_add_f32 v[32:33], v[32:33], v[54:55]
	v_lshlrev_b32_e32 v54, 16, v94
	v_and_b32_e32 v55, 0xffff0000, v94
	v_pk_add_f32 v[38:39], v[38:39], v[54:55]
	v_lshlrev_b32_e32 v54, 16, v95
	v_and_b32_e32 v55, 0xffff0000, v95
	v_pk_add_f32 v[36:37], v[36:37], v[58:59]
	v_pk_add_f32 v[40:41], v[40:41], v[54:55]
	v_cmp_le_u32_e32 vcc, 9, v2
	s_nop 1
	s_and_b64 exec, s[44:45], vcc
	s_cbranch_execz .Lpool_done
	v_lshlrev_b32_e32 v58, 16, v96
	v_and_b32_e32 v59, 0xffff0000, v96
	v_lshlrev_b32_e32 v54, 16, v97
	v_and_b32_e32 v55, 0xffff0000, v97
	v_pk_add_f32 v[32:33], v[32:33], v[54:55]
	v_lshlrev_b32_e32 v54, 16, v98
	v_and_b32_e32 v55, 0xffff0000, v98
	v_pk_add_f32 v[38:39], v[38:39], v[54:55]
	v_lshlrev_b32_e32 v54, 16, v99
	v_and_b32_e32 v55, 0xffff0000, v99
	v_pk_add_f32 v[36:37], v[36:37], v[58:59]
	v_pk_add_f32 v[40:41], v[40:41], v[54:55]
	v_cmp_le_u32_e32 vcc, 10, v2
	s_nop 1
	s_and_b64 exec, s[44:45], vcc
	s_cbranch_execz .Lpool_done
	v_lshlrev_b32_e32 v58, 16, v100
	v_and_b32_e32 v59, 0xffff0000, v100
	v_lshlrev_b32_e32 v54, 16, v101
	v_and_b32_e32 v55, 0xffff0000, v101
	v_pk_add_f32 v[32:33], v[32:33], v[54:55]
	v_lshlrev_b32_e32 v54, 16, v102
	v_and_b32_e32 v55, 0xffff0000, v102
	v_pk_add_f32 v[38:39], v[38:39], v[54:55]
	v_lshlrev_b32_e32 v54, 16, v103
	v_and_b32_e32 v55, 0xffff0000, v103
	v_pk_add_f32 v[36:37], v[36:37], v[58:59]
	v_pk_add_f32 v[40:41], v[40:41], v[54:55]
	v_cmp_le_u32_e32 vcc, 11, v2
	s_nop 1
	s_and_b64 exec, s[44:45], vcc
	s_cbranch_execz .Lpool_done
	v_lshlrev_b32_e32 v58, 16, v104
	v_and_b32_e32 v59, 0xffff0000, v104
	v_lshlrev_b32_e32 v54, 16, v105
	v_and_b32_e32 v55, 0xffff0000, v105
	v_pk_add_f32 v[32:33], v[32:33], v[54:55]
	v_lshlrev_b32_e32 v54, 16, v106
	v_and_b32_e32 v55, 0xffff0000, v106
	v_pk_add_f32 v[38:39], v[38:39], v[54:55]
	v_lshlrev_b32_e32 v54, 16, v107
	v_and_b32_e32 v55, 0xffff0000, v107
	v_pk_add_f32 v[36:37], v[36:37], v[58:59]
	v_pk_add_f32 v[40:41], v[40:41], v[54:55]
	v_cmp_le_u32_e32 vcc, 12, v2
	s_nop 1
	s_and_b64 exec, s[44:45], vcc
	s_cbranch_execz .Lpool_done
	v_lshlrev_b32_e32 v58, 16, v108
	v_and_b32_e32 v59, 0xffff0000, v108
	v_lshlrev_b32_e32 v54, 16, v109
	v_and_b32_e32 v55, 0xffff0000, v109
	v_pk_add_f32 v[32:33], v[32:33], v[54:55]
	v_lshlrev_b32_e32 v54, 16, v110
	v_and_b32_e32 v55, 0xffff0000, v110
	v_pk_add_f32 v[38:39], v[38:39], v[54:55]
	v_lshlrev_b32_e32 v54, 16, v111
	v_and_b32_e32 v55, 0xffff0000, v111
	v_pk_add_f32 v[36:37], v[36:37], v[58:59]
	v_pk_add_f32 v[40:41], v[40:41], v[54:55]
	v_cmp_le_u32_e32 vcc, 13, v2
	s_nop 1
	s_and_b64 exec, s[44:45], vcc
	s_cbranch_execz .Lpool_done
	v_lshlrev_b32_e32 v58, 16, v112
	v_and_b32_e32 v59, 0xffff0000, v112
	v_lshlrev_b32_e32 v54, 16, v113
	v_and_b32_e32 v55, 0xffff0000, v113
	v_pk_add_f32 v[32:33], v[32:33], v[54:55]
	v_lshlrev_b32_e32 v54, 16, v114
	v_and_b32_e32 v55, 0xffff0000, v114
	v_pk_add_f32 v[38:39], v[38:39], v[54:55]
	v_lshlrev_b32_e32 v54, 16, v115
	v_and_b32_e32 v55, 0xffff0000, v115
	v_pk_add_f32 v[36:37], v[36:37], v[58:59]
	v_pk_add_f32 v[40:41], v[40:41], v[54:55]
	v_cmp_le_u32_e32 vcc, 14, v2
	s_nop 1
	s_and_b64 exec, s[44:45], vcc
	s_cbranch_execz .Lpool_done
	v_lshlrev_b32_e32 v58, 16, v116
	v_and_b32_e32 v59, 0xffff0000, v116
	v_lshlrev_b32_e32 v54, 16, v117
	v_and_b32_e32 v55, 0xffff0000, v117
	v_pk_add_f32 v[32:33], v[32:33], v[54:55]
	v_lshlrev_b32_e32 v54, 16, v118
	v_and_b32_e32 v55, 0xffff0000, v118
	v_pk_add_f32 v[38:39], v[38:39], v[54:55]
	v_lshlrev_b32_e32 v54, 16, v119
	v_and_b32_e32 v55, 0xffff0000, v119
	v_pk_add_f32 v[36:37], v[36:37], v[58:59]
	v_pk_add_f32 v[40:41], v[40:41], v[54:55]
	v_cmp_le_u32_e32 vcc, 15, v2
	s_nop 1
	s_and_b64 exec, s[44:45], vcc
	s_cbranch_execz .Lpool_done
	v_lshlrev_b32_e32 v58, 16, v120
	v_and_b32_e32 v59, 0xffff0000, v120
	v_lshlrev_b32_e32 v54, 16, v121
	v_and_b32_e32 v55, 0xffff0000, v121
	v_pk_add_f32 v[32:33], v[32:33], v[54:55]
	v_lshlrev_b32_e32 v54, 16, v122
	v_and_b32_e32 v55, 0xffff0000, v122
	v_pk_add_f32 v[38:39], v[38:39], v[54:55]
	v_lshlrev_b32_e32 v54, 16, v123
	v_and_b32_e32 v55, 0xffff0000, v123
	v_pk_add_f32 v[36:37], v[36:37], v[58:59]
	v_pk_add_f32 v[40:41], v[40:41], v[54:55]
